# speedup vs baseline: 1.0526x; 1.0047x over previous
; __device__ __forceinline__ bf16x8 gld16(const void* p) { bf16x8 v; asm volatile("global_load_dwordx4 %0, %1, off" : "=v"(v) : "v"(p) : "memory"); return v; }
;   __device__ __forceinline__ bfu* pb() const { return (bfu*)(b + L::o_pb); }
;   __device__ __forceinline__ float* gl() const { return (float*)(b + L::o_gl); }
;   __device__ __forceinline__ bfu* rb() const { return (bfu*)(b + L::o_rb); }
; template <bool SWAP>
; __device__ __forceinline__ void gemm_big(const bfu* __restrict__ A, int lda, const bfu* __restrict__ B, int ldb, int K,
;                                          f32x4 (&acc)[8][4], bfu* sm, const bfu* An = nullptr, const bfu* Bn = nullptr) {
;     ...
;   const int lrow = tid >> 2, lch = (tid & 3) * 8;
;   const bfu* Ap = A + (size_t)lrow * lda + lch;
;   const bfu* Bp = B + (size_t)lrow * ldb + lch;
;   int brow = lrow;
;   if (SWAP) brow = ((lrow & 12) << 2) | ((lrow >> 2) & 12) | (lrow & 3);
;   const int nk = K >> 5;
;   const bool chain = (An != nullptr);
;   const bfu* Apn = chain ? (An + (size_t)lrow * lda + lch) : Ap;
;   const bfu* Bpn = chain ? (Bn + (size_t)lrow * ldb + lch) : Bp;
;   auto gl = [&](bf16x8 (&ra)[4], bf16x8 (&rb)[2], int kt) {
;     const bool nx = (kt >= nk);
;     const bfu* pa = nx ? (chain ? Apn + (kt - nk) * 32 : Ap + (nk - 1) * 32) : Ap + kt * 32;
;     const bfu* pb = nx ? (chain ? Bpn + (kt - nk) * 32 : Bp + (nk - 1) * 32) : Bp + kt * 32;
; #pragma unroll
;     for (int q = 0; q < 4; ++q) ra[q] = gld16(pa + (size_t)(64 * q) * lda);
; #pragma unroll
;     for (int q = 0; q < 2; ++q) rb[q] = gld16(pb + (size_t)(64 * q) * ldb);
;   };
;   auto wt = [&](bf16x8 (&ra)[4], bf16x8 (&rb)[2]) {
;     asm volatile("s_waitcnt vmcnt(6)" : "+v"(ra[0]), "+v"(ra[1]), "+v"(ra[2]), "+v"(ra[3]), "+v"(rb[0]), "+v"(rb[1]) : : "memory");
;   };
;   auto st = [&](const bf16x8 (&ra)[4], const bf16x8 (&rb)[2], int buf) {
; #pragma unroll
;     for (int q = 0; q < 4; ++q) *(bf16x8*)(As + (buf * 256 + lrow + 64 * q) * 40 + lch) = ra[q];
; #pragma unroll
;     for (int q = 0; q < 2; ++q) *(bf16x8*)(Bs + (buf * 128 + brow + 64 * q) * 40 + lch) = rb[q];
;     ...
;   gl(ra0, rb0, 0);
;   gl(ra1, rb1, 1);
;   __syncthreads();
;   wt(ra0, rb0);
;   st(ra0, rb0, 0);
;   __syncthreads();
.LBB0_109:
	v_mov_b32_e32 v27, v174
	s_mov_b64 s[0:1], 0x20040
	v_ashrrev_i32_e32 v24, 2, v27
	v_ashrrev_i32_e32 v25, 31, v24
	v_lshlrev_b64 v[0:1], 11, v[24:25]
	v_lshlrev_b32_e32 v4, 4, v27
	v_lshl_add_u64 v[2:3], s[18:19], 0, v[0:1]
	v_and_b32_e32 v152, 48, v4
	v_lshl_add_u64 v[164:165], v[2:3], 0, v[152:153]
	v_lshl_add_u64 v[2:3], s[20:21], 0, v[0:1]
	v_lshl_add_u64 v[166:167], v[2:3], 0, v[152:153]
	v_lshrrev_b32_e32 v2, 2, v24
	v_and_b32_e32 v26, 48, v27
	v_and_b32_e32 v2, 12, v2
	v_and_b32_e32 v3, 3, v24
	v_or3_b32 v25, v26, v3, v2
	v_lshl_add_u64 v[2:3], s[22:23], 0, v[0:1]
	v_lshl_add_u64 v[0:1], s[24:25], 0, v[0:1]
	v_lshl_add_u64 v[28:29], v[2:3], 0, v[152:153]
	v_lshl_add_u64 v[30:31], v[0:1], 0, v[152:153]
	global_load_dwordx4 v[0:3], v[164:165], off
	v_lshl_add_u64 v[4:5], v[164:165], 0, s[8:9]
	global_load_dwordx4 v[4:7], v[4:5], off
	v_lshl_add_u64 v[8:9], v[164:165], 0, s[4:5]
	global_load_dwordx4 v[8:11], v[8:9], off
	v_lshl_add_u64 v[12:13], v[164:165], 0, s[90:91]
	global_load_dwordx4 v[12:15], v[12:13], off
	global_load_dwordx4 v[16:19], v[166:167], off
	v_lshl_add_u64 v[20:21], v[166:167], 0, s[8:9]
	global_load_dwordx4 v[20:23], v[20:21], off
	v_lshl_add_u64 v[32:33], v[164:165], 0, 64
	global_load_dwordx4 v[128:131], v[32:33], off
	v_lshl_add_u64 v[32:33], v[164:165], 0, s[0:1]
	global_load_dwordx4 v[132:135], v[32:33], off
	s_mov_b64 s[28:29], 0x40040
	v_lshl_add_u64 v[32:33], v[164:165], 0, s[28:29]
	global_load_dwordx4 v[136:139], v[32:33], off
	s_mov_b64 s[28:29], 0x60040
	v_lshl_add_u64 v[32:33], v[164:165], 0, s[28:29]
	global_load_dwordx4 v[140:143], v[32:33], off
	v_lshl_add_u64 v[34:35], v[166:167], 0, 64
	global_load_dwordx4 v[144:147], v[34:35], off
	v_lshl_add_u64 v[32:33], v[166:167], 0, s[0:1]
	global_load_dwordx4 v[148:151], v[32:33], off
	s_barrier
	s_waitcnt vmcnt(6)
	s_movk_i32 s2, 0x40
	v_and_b32_e32 v36, 8, v24
	v_mul_u32_u24_e32 v36, 6, v36
	s_nop 0
	v_xor_b32_e32 v36, v152, v36
	v_mad_u32_u24 v168, v24, s2, v36
	ds_write_b128 v168, v[0:3]
	ds_write_b128 v168, v[4:7] offset:4096
	ds_write_b128 v168, v[8:11] offset:8192
	ds_write_b128 v168, v[12:15] offset:12288
	v_and_b32_e32 v0, 0xfffff8f, v27
	v_and_b32_e32 v1, 0x4f, v27
	v_and_b32_e32 v37, 8, v25
	v_mul_u32_u24_e32 v37, 6, v37
	s_nop 0
	v_xor_b32_e32 v37, v152, v37
	v_mad_u32_u24 v169, v25, s2, v37
	v_mul_u32_u24_e32 v1, 32, v1
	v_and_b32_e32 v38, 8, v27
	v_mul_u32_u24_e32 v38, 6, v38
	s_nop 0
	v_xor_b32_e32 v38, v26, v38
	v_mad_u32_u24 v172, v0, s2, v38
	v_mov_b32_e32 v0, 0
	ds_write_b128 v169, v[16:19] offset:32768
	ds_write_b128 v169, v[20:23] offset:36864
	v_cndmask_b32_e64 v157, v29, v165, s[10:11]
	v_cndmask_b32_e64 v152, v28, v164, s[10:11]
	v_cndmask_b32_e64 v159, v31, v167, s[10:11]
	v_cndmask_b32_e64 v170, v30, v166, s[10:11]
	v_lshl_add_u32 v199, v1, 1, v38
	s_mov_b32 s17, 0
	s_movk_i32 s15, 0xfc40
	v_mov_b32_e32 v1, v0
	v_mov_b32_e32 v2, v0
	v_mov_b32_e32 v3, v0
	v_mov_b32_e32 v4, v0
	v_mov_b32_e32 v5, v0
	v_mov_b32_e32 v6, v0
	v_mov_b32_e32 v7, v0
	v_mov_b32_e32 v8, v0
	v_mov_b32_e32 v9, v0
	v_mov_b32_e32 v10, v0
	v_mov_b32_e32 v11, v0
	v_mov_b32_e32 v12, v0
	v_mov_b32_e32 v13, v0
	v_mov_b32_e32 v14, v0
	v_mov_b32_e32 v15, v0
	v_mov_b32_e32 v16, v0
	v_mov_b32_e32 v17, v0
	v_mov_b32_e32 v18, v0
	v_mov_b32_e32 v19, v0
	v_mov_b32_e32 v20, v0
	v_mov_b32_e32 v21, v0
	v_mov_b32_e32 v22, v0
	v_mov_b32_e32 v23, v0
	v_mov_b32_e32 v24, v0
	v_mov_b32_e32 v25, v0
	v_mov_b32_e32 v26, v0
	v_mov_b32_e32 v27, v0
	v_mov_b32_e32 v28, v0
	v_mov_b32_e32 v29, v0
	v_mov_b32_e32 v30, v0
	v_mov_b32_e32 v31, v0
	v_mov_b32_e32 v32, v0
	v_mov_b32_e32 v33, v0
	v_mov_b32_e32 v34, v0
	v_mov_b32_e32 v35, v0
	v_mov_b32_e32 v36, v0
	v_mov_b32_e32 v37, v0
	v_mov_b32_e32 v38, v0
	v_mov_b32_e32 v39, v0
	v_mov_b32_e32 v40, v0
	v_mov_b32_e32 v41, v0
	v_mov_b32_e32 v42, v0
	v_mov_b32_e32 v43, v0
	v_mov_b32_e32 v44, v0
	v_mov_b32_e32 v45, v0
	v_mov_b32_e32 v46, v0
	v_mov_b32_e32 v47, v0
	v_mov_b32_e32 v48, v0
	v_mov_b32_e32 v49, v0
	v_mov_b32_e32 v50, v0
	v_mov_b32_e32 v51, v0
	v_mov_b32_e32 v52, v0
	v_mov_b32_e32 v53, v0
	v_mov_b32_e32 v54, v0
	v_mov_b32_e32 v55, v0
	v_mov_b32_e32 v56, v0
	v_mov_b32_e32 v57, v0
	v_mov_b32_e32 v58, v0
	v_mov_b32_e32 v59, v0
	v_mov_b32_e32 v60, v0
	v_mov_b32_e32 v61, v0
	v_mov_b32_e32 v62, v0
	v_mov_b32_e32 v63, v0
	v_mov_b32_e32 v64, v0
	v_mov_b32_e32 v65, v0
	v_mov_b32_e32 v66, v0
	v_mov_b32_e32 v67, v0
	v_mov_b32_e32 v68, v0
	v_mov_b32_e32 v69, v0
	v_mov_b32_e32 v70, v0
	v_mov_b32_e32 v71, v0
	v_mov_b32_e32 v72, v0
	v_mov_b32_e32 v73, v0
	v_mov_b32_e32 v74, v0
	v_mov_b32_e32 v75, v0
	v_mov_b32_e32 v76, v0
	v_mov_b32_e32 v77, v0
	v_mov_b32_e32 v78, v0
	v_mov_b32_e32 v79, v0
	v_mov_b32_e32 v80, v0
	v_mov_b32_e32 v81, v0
	v_mov_b32_e32 v82, v0
	v_mov_b32_e32 v83, v0
	v_mov_b32_e32 v84, v0
	v_mov_b32_e32 v85, v0
	v_mov_b32_e32 v86, v0
	v_mov_b32_e32 v87, v0
	v_mov_b32_e32 v88, v0
	v_mov_b32_e32 v89, v0
	v_mov_b32_e32 v90, v0
	v_mov_b32_e32 v91, v0
	v_mov_b32_e32 v92, v0
	v_mov_b32_e32 v93, v0
	v_mov_b32_e32 v94, v0
	v_mov_b32_e32 v95, v0
	v_mov_b32_e32 v96, v0
	v_mov_b32_e32 v97, v0
	v_mov_b32_e32 v98, v0
	v_mov_b32_e32 v99, v0
	v_mov_b32_e32 v100, v0
	v_mov_b32_e32 v101, v0
	v_mov_b32_e32 v102, v0
	v_mov_b32_e32 v103, v0
	v_mov_b32_e32 v104, v0
	v_mov_b32_e32 v105, v0
	v_mov_b32_e32 v106, v0
	v_mov_b32_e32 v107, v0
	v_mov_b32_e32 v108, v0
	v_mov_b32_e32 v109, v0
	v_mov_b32_e32 v110, v0
	v_mov_b32_e32 v111, v0
	v_mov_b32_e32 v112, v0
	v_mov_b32_e32 v113, v0
	v_mov_b32_e32 v114, v0
	v_mov_b32_e32 v115, v0
	v_mov_b32_e32 v116, v0
	v_mov_b32_e32 v117, v0
	v_mov_b32_e32 v118, v0
	v_mov_b32_e32 v119, v0
	v_mov_b32_e32 v120, v0
	v_mov_b32_e32 v121, v0
	v_mov_b32_e32 v122, v0
	v_mov_b32_e32 v123, v0
	v_mov_b32_e32 v124, v0
	v_mov_b32_e32 v125, v0
	v_mov_b32_e32 v126, v0
	v_mov_b32_e32 v127, v0
	s_waitcnt lgkmcnt(0)
	s_barrier
; #define MFMA16(a, b, c) __builtin_amdgcn_mfma_f32_16x16x32_bf16((a), (b), (c), 0, 0, 0)
;   __device__ __forceinline__ float* gl() const { return (float*)(b + L::o_gl); }
; template <bool SWAP>
; __device__ __forceinline__ void gemm_big(const bfu* __restrict__ A, int lda, const bfu* __restrict__ B, int ldb, int K,
;                                          f32x4 (&acc)[8][4], bfu* sm, const bfu* An = nullptr, const bfu* Bn = nullptr) {
;     ...
;   auto comp = [&](int buf, auto&& mid) {
;     const bfu* as = As + buf * 256 * 40 + (wr * 128 + c15) * 40 + g * 8;
;     const bfu* bs = Bs + buf * 128 * 40 + (wc * 64 + c15) * 40 + g * 8;
;     bf16x8 b[4];
; #pragma unroll
;     for (int j = 0; j < 4; ++j) b[j] = *(const bf16x8*)(bs + j * 16 * 40);
;     {
;       bf16x8 a[4];
; #pragma unroll
;       for (int i = 0; i < 4; ++i) a[i] = *(const bf16x8*)(as + i * 16 * 40);
;       mid();
;       __builtin_amdgcn_s_setprio(1);
; #pragma unroll
;       for (int i = 0; i < 4; ++i)
; #pragma unroll
;         for (int j = 0; j < 4; ++j) acc[i][j] = SWAP ? MFMA16(b[j], a[i], acc[i][j]) : MFMA16(a[i], b[j], acc[i][j]);
;       __builtin_amdgcn_s_setprio(0);
;     }
;     {
;       bf16x8 a[4];
; #pragma unroll
;       for (int i = 0; i < 4; ++i) a[i] = *(const bf16x8*)(as + (i + 4) * 16 * 40);
;       __builtin_amdgcn_s_setprio(1);
; #pragma unroll
;       for (int i = 0; i < 4; ++i)
; #pragma unroll
;         for (int j = 0; j < 4; ++j) acc[i + 4][j] = SWAP ? MFMA16(b[j], a[i], acc[i + 4][j]) : MFMA16(a[i], b[j], acc[i + 4][j]);
;       __builtin_amdgcn_s_setprio(0);
;     }
;   };
;   gl(ra0, rb0, 0);
;   gl(ra1, rb1, 1);
;   __syncthreads();
;   wt(ra0, rb0);
;   st(ra0, rb0, 0);
;   __syncthreads();
;   for (int kt = 0; kt < nk; kt += 2) {
;     gl(ra0, rb0, kt + 2);
;     comp(0, [&]() { wt(ra1, rb1); st(ra1, rb1, 1); });
.LBB0_110:
	s_add_i32 s27, s17, 2
	s_cmp_lt_u32 s17, 30
	s_cselect_b64 s[0:1], -1, 0
	s_add_i32 s2, s15, 0x400
	s_and_b64 s[28:29], s[10:11], exec
	s_cselect_b32 s28, 0x3e0, s15
	s_and_b64 vcc, s[0:1], exec
	s_cselect_b32 s2, s2, s28
	v_cndmask_b32_e64 v185, v157, v165, s[0:1]
	v_cndmask_b32_e64 v184, v152, v164, s[0:1]
	v_cndmask_b32_e64 v187, v159, v167, s[0:1]
	v_cndmask_b32_e64 v186, v170, v166, s[0:1]
	s_lshl_b64 s[0:1], s[2:3], 1
	v_lshl_add_u64 v[208:209], v[184:185], 0, s[0:1]
	v_lshl_add_u64 v[216:217], v[186:187], 0, s[0:1]
	ds_read_b128 v[220:223], v199 offset:32768
	ds_read_b128 v[224:227], v199 offset:33792
	ds_read_b128 v[228:231], v199 offset:34816
	ds_read_b128 v[232:235], v199 offset:35840
	ds_read_b128 v[236:239], v172
	ds_read_b128 v[240:243], v172 offset:1024
	ds_read_b128 v[244:247], v172 offset:2048
	ds_read_b128 v[248:251], v172 offset:3072
	s_waitcnt vmcnt(0)
	ds_write_b128 v168, v[128:131] offset:16384
	ds_write_b128 v168, v[132:135] offset:20480
	ds_write_b128 v168, v[136:139] offset:24576
	ds_write_b128 v168, v[140:143] offset:28672
	ds_write_b128 v169, v[144:147] offset:40960
	ds_write_b128 v169, v[148:151] offset:45056
	s_cmp_lt_u32 s17, 29
	s_cselect_b64 s[0:1], -1, 0
	s_add_i32 s2, s15, 0x420
	s_add_i32 s17, s15, 32
	s_and_b64 s[28:29], s[10:11], exec
	s_cselect_b32 s17, 0x3e0, s17
	s_and_b64 s[28:29], s[0:1], exec
	s_cselect_b32 s2, s2, s17
	v_cndmask_b32_e64 v129, v157, v165, s[0:1]
	v_cndmask_b32_e64 v128, v152, v164, s[0:1]
	v_cndmask_b32_e64 v131, v159, v167, s[0:1]
	v_cndmask_b32_e64 v130, v170, v166, s[0:1]
	s_lshl_b64 s[0:1], s[2:3], 1
	v_lshl_add_u64 v[140:141], v[128:129], 0, s[0:1]
	v_lshl_add_u64 v[148:149], v[130:131], 0, s[0:1]
	s_setprio 1
	s_waitcnt lgkmcnt(9)
	v_mfma_f32_16x16x32_bf16 v[124:127], v[220:223], v[236:239], v[124:127]
	global_load_dwordx4 v[184:187], v[208:209], off
	v_mfma_f32_16x16x32_bf16 v[120:123], v[224:227], v[236:239], v[120:123]
	global_load_dwordx4 v[128:131], v[140:141], off
	v_mfma_f32_16x16x32_bf16 v[116:119], v[228:231], v[236:239], v[116:119]
	v_lshl_add_u64 v[200:201], v[208:209], 0, s[8:9]
	global_load_dwordx4 v[200:203], v[200:201], off
	v_mfma_f32_16x16x32_bf16 v[112:115], v[232:235], v[236:239], v[112:115]
	v_lshl_add_u64 v[132:133], v[140:141], 0, s[8:9]
	global_load_dwordx4 v[132:135], v[132:133], off
	s_waitcnt lgkmcnt(8)
	v_mfma_f32_16x16x32_bf16 v[108:111], v[220:223], v[240:243], v[108:111]
	v_lshl_add_u64 v[204:205], v[208:209], 0, s[4:5]
	global_load_dwordx4 v[204:207], v[204:205], off
	v_mfma_f32_16x16x32_bf16 v[104:107], v[224:227], v[240:243], v[104:107]
	v_lshl_add_u64 v[136:137], v[140:141], 0, s[4:5]
	global_load_dwordx4 v[136:139], v[136:137], off
	v_mfma_f32_16x16x32_bf16 v[100:103], v[228:231], v[240:243], v[100:103]
	v_lshl_add_u64 v[208:209], v[208:209], 0, s[90:91]
	global_load_dwordx4 v[208:211], v[208:209], off
	v_mfma_f32_16x16x32_bf16 v[96:99], v[232:235], v[240:243], v[96:99]
	v_lshl_add_u64 v[140:141], v[140:141], 0, s[90:91]
	global_load_dwordx4 v[140:143], v[140:141], off
	s_waitcnt lgkmcnt(7)
	v_mfma_f32_16x16x32_bf16 v[92:95], v[220:223], v[244:247], v[92:95]
	global_load_dwordx4 v[212:215], v[216:217], off
	v_mfma_f32_16x16x32_bf16 v[88:91], v[224:227], v[244:247], v[88:91]
	global_load_dwordx4 v[144:147], v[148:149], off
	v_mfma_f32_16x16x32_bf16 v[84:87], v[228:231], v[244:247], v[84:87]
	v_lshl_add_u64 v[216:217], v[216:217], 0, s[8:9]
	global_load_dwordx4 v[216:219], v[216:217], off
	v_mfma_f32_16x16x32_bf16 v[80:83], v[232:235], v[244:247], v[80:83]
	v_lshl_add_u64 v[148:149], v[148:149], 0, s[8:9]
	global_load_dwordx4 v[148:151], v[148:149], off
	s_waitcnt lgkmcnt(6)
	v_mfma_f32_16x16x32_bf16 v[76:79], v[220:223], v[248:251], v[76:79]
	v_mfma_f32_16x16x32_bf16 v[72:75], v[224:227], v[248:251], v[72:75]
	v_mfma_f32_16x16x32_bf16 v[68:71], v[228:231], v[248:251], v[68:71]
	v_mfma_f32_16x16x32_bf16 v[64:67], v[232:235], v[248:251], v[64:67]
	s_setprio 0
	ds_read_b128 v[236:239], v172 offset:4096
	ds_read_b128 v[240:243], v172 offset:5120
	ds_read_b128 v[244:247], v172 offset:6144
	ds_read_b128 v[248:251], v172 offset:7168
	s_setprio 1
	s_waitcnt lgkmcnt(3)
	v_mfma_f32_16x16x32_bf16 v[60:63], v[220:223], v[236:239], v[60:63]
	v_mfma_f32_16x16x32_bf16 v[56:59], v[224:227], v[236:239], v[56:59]
	v_mfma_f32_16x16x32_bf16 v[52:55], v[228:231], v[236:239], v[52:55]
	v_mfma_f32_16x16x32_bf16 v[48:51], v[232:235], v[236:239], v[48:51]
	s_waitcnt lgkmcnt(2)
	v_mfma_f32_16x16x32_bf16 v[44:47], v[220:223], v[240:243], v[44:47]
	v_mfma_f32_16x16x32_bf16 v[40:43], v[224:227], v[240:243], v[40:43]
	v_mfma_f32_16x16x32_bf16 v[36:39], v[228:231], v[240:243], v[36:39]
	v_mfma_f32_16x16x32_bf16 v[32:35], v[232:235], v[240:243], v[32:35]
	s_waitcnt lgkmcnt(1)
	v_mfma_f32_16x16x32_bf16 v[28:31], v[220:223], v[244:247], v[28:31]
	v_mfma_f32_16x16x32_bf16 v[24:27], v[224:227], v[244:247], v[24:27]
	v_mfma_f32_16x16x32_bf16 v[20:23], v[228:231], v[244:247], v[20:23]
	v_mfma_f32_16x16x32_bf16 v[16:19], v[232:235], v[244:247], v[16:19]
	s_waitcnt lgkmcnt(0)
	v_mfma_f32_16x16x32_bf16 v[12:15], v[220:223], v[248:251], v[12:15]
	v_mfma_f32_16x16x32_bf16 v[8:11], v[224:227], v[248:251], v[8:11]
	v_mfma_f32_16x16x32_bf16 v[4:7], v[228:231], v[248:251], v[4:7]
	v_mfma_f32_16x16x32_bf16 v[0:3], v[232:235], v[248:251], v[0:3]
	s_setprio 0
	s_barrier
; #define MFMA16(a, b, c) __builtin_amdgcn_mfma_f32_16x16x32_bf16((a), (b), (c), 0, 0, 0)
;   __device__ __forceinline__ float* small() const { return (float*)(b + L::o_small); }
; template <bool SWAP>
; __device__ __forceinline__ void gemm_big(const bfu* __restrict__ A, int lda, const bfu* __restrict__ B, int ldb, int K,
;                                          f32x4 (&acc)[8][4], bfu* sm, const bfu* An = nullptr, const bfu* Bn = nullptr) {
;     ...
;     {
;       bf16x8 a[4];
; #pragma unroll
;       for (int i = 0; i < 4; ++i) a[i] = *(const bf16x8*)(as + (i + 4) * 16 * 40);
;       __builtin_amdgcn_s_setprio(1);
; #pragma unroll
;       for (int i = 0; i < 4; ++i)
; #pragma unroll
;         for (int j = 0; j < 4; ++j) acc[i + 4][j] = SWAP ? MFMA16(b[j], a[i], acc[i + 4][j]) : MFMA16(a[i], b[j], acc[i + 4][j]);
;       __builtin_amdgcn_s_setprio(0);
;     }
;   };
; template <int G>
; __device__ __forceinline__ void p1_big(const Params& P, const Ptrs<G>& w, int layer, int mt, int nt, bfu* sm, int mtn, int ntn) {
;     ...
;       if (wc == 0 && g == 0) {
; #pragma unroll
;         for (int i = 0; i < 8; ++i) {
;           float* sp = w.small() + (size_t)(m0 + wr * 128 + 16 * i + c15) * 16;
; #pragma unroll
;           for (int j = 0; j < 4; ++j) *(float4*)(sp + 4 * j) = make_float4(acc[i][j][0], acc[i][j][1], acc[i][j][2], acc[i][j][3]);
;         }
;       }
	ds_read_b128 v[220:223], v199 offset:40960
	ds_read_b128 v[224:227], v199 offset:41984
	ds_read_b128 v[228:231], v199 offset:43008
	ds_read_b128 v[232:235], v199 offset:44032
	ds_read_b128 v[236:239], v172 offset:16384
	ds_read_b128 v[240:243], v172 offset:17408
	ds_read_b128 v[244:247], v172 offset:18432
	ds_read_b128 v[248:251], v172 offset:19456
	s_setprio 1
	s_waitcnt lgkmcnt(3)
	v_mfma_f32_16x16x32_bf16 v[124:127], v[220:223], v[236:239], v[124:127]
	v_mfma_f32_16x16x32_bf16 v[120:123], v[224:227], v[236:239], v[120:123]
	v_mfma_f32_16x16x32_bf16 v[116:119], v[228:231], v[236:239], v[116:119]
	v_mfma_f32_16x16x32_bf16 v[112:115], v[232:235], v[236:239], v[112:115]
	s_waitcnt lgkmcnt(2)
	v_mfma_f32_16x16x32_bf16 v[108:111], v[220:223], v[240:243], v[108:111]
	v_mfma_f32_16x16x32_bf16 v[104:107], v[224:227], v[240:243], v[104:107]
	v_mfma_f32_16x16x32_bf16 v[100:103], v[228:231], v[240:243], v[100:103]
	v_mfma_f32_16x16x32_bf16 v[96:99], v[232:235], v[240:243], v[96:99]
	s_waitcnt lgkmcnt(1)
	v_mfma_f32_16x16x32_bf16 v[92:95], v[220:223], v[244:247], v[92:95]
	v_mfma_f32_16x16x32_bf16 v[88:91], v[224:227], v[244:247], v[88:91]
	v_mfma_f32_16x16x32_bf16 v[84:87], v[228:231], v[244:247], v[84:87]
	v_mfma_f32_16x16x32_bf16 v[80:83], v[232:235], v[244:247], v[80:83]
	s_waitcnt lgkmcnt(0)
	v_mfma_f32_16x16x32_bf16 v[76:79], v[220:223], v[248:251], v[76:79]
	v_mfma_f32_16x16x32_bf16 v[72:75], v[224:227], v[248:251], v[72:75]
	v_mfma_f32_16x16x32_bf16 v[68:71], v[228:231], v[248:251], v[68:71]
	v_mfma_f32_16x16x32_bf16 v[64:67], v[232:235], v[248:251], v[64:67]
	s_setprio 0
	s_waitcnt vmcnt(1)
	ds_write_b128 v168, v[184:187]
	ds_write_b128 v168, v[200:203] offset:4096
	ds_write_b128 v168, v[204:207] offset:8192
	ds_write_b128 v168, v[208:211] offset:12288
	ds_write_b128 v169, v[212:215] offset:32768
	ds_write_b128 v169, v[216:219] offset:36864
	ds_read_b128 v[236:239], v172 offset:20480
	ds_read_b128 v[240:243], v172 offset:21504
	ds_read_b128 v[244:247], v172 offset:22528
	ds_read_b128 v[248:251], v172 offset:23552
	s_setprio 1
	s_waitcnt lgkmcnt(3)
	v_mfma_f32_16x16x32_bf16 v[60:63], v[220:223], v[236:239], v[60:63]
	v_mfma_f32_16x16x32_bf16 v[56:59], v[224:227], v[236:239], v[56:59]
	v_mfma_f32_16x16x32_bf16 v[52:55], v[228:231], v[236:239], v[52:55]
	v_mfma_f32_16x16x32_bf16 v[48:51], v[232:235], v[236:239], v[48:51]
	s_waitcnt lgkmcnt(2)
	v_mfma_f32_16x16x32_bf16 v[44:47], v[220:223], v[240:243], v[44:47]
	v_mfma_f32_16x16x32_bf16 v[40:43], v[224:227], v[240:243], v[40:43]
	v_mfma_f32_16x16x32_bf16 v[36:39], v[228:231], v[240:243], v[36:39]
	v_mfma_f32_16x16x32_bf16 v[32:35], v[232:235], v[240:243], v[32:35]
	s_waitcnt lgkmcnt(1)
	v_mfma_f32_16x16x32_bf16 v[28:31], v[220:223], v[244:247], v[28:31]
	v_mfma_f32_16x16x32_bf16 v[24:27], v[224:227], v[244:247], v[24:27]
	v_mfma_f32_16x16x32_bf16 v[20:23], v[228:231], v[244:247], v[20:23]
	v_mfma_f32_16x16x32_bf16 v[16:19], v[232:235], v[244:247], v[16:19]
	s_waitcnt lgkmcnt(0)
	v_mfma_f32_16x16x32_bf16 v[12:15], v[220:223], v[248:251], v[12:15]
	v_mfma_f32_16x16x32_bf16 v[8:11], v[224:227], v[248:251], v[8:11]
	v_mfma_f32_16x16x32_bf16 v[4:7], v[228:231], v[248:251], v[4:7]
	v_mfma_f32_16x16x32_bf16 v[0:3], v[232:235], v[248:251], v[0:3]
	s_setprio 0
	s_add_i32 s15, s15, 64
	s_mov_b32 s17, s27
	s_barrier
	s_cbranch_vccnz .LBB0_110
	s_waitcnt vmcnt(0)
	s_cmpk_gt_i32 s26, 0xcff
	s_mov_b64 s[0:1], -1
	s_cbranch_scc0 .LBB0_115
	v_or_b32_e32 v128, v161, v163
	v_cmp_eq_u32_e32 vcc, 0, v128
	s_and_saveexec_b64 s[0:1], vcc
	s_cbranch_execz .LBB0_114
	v_and_b32_e32 v128, 0xffffff80, v198
	v_add_u32_e32 v128, s16, v128
	v_or_b32_e32 v128, v128, v171
	v_ashrrev_i32_e32 v129, 31, v128
	v_lshlrev_b64 v[130:131], 6, v[128:129]
	v_lshl_add_u64 v[130:131], s[62:63], 0, v[130:131]
	global_store_dwordx4 v[130:131], v[124:127], off
	global_store_dwordx4 v[130:131], v[120:123], off offset:16
	global_store_dwordx4 v[130:131], v[116:119], off offset:32
	global_store_dwordx4 v[130:131], v[112:115], off offset:48
	v_or_b32_e32 v130, 16, v128
	v_ashrrev_i32_e32 v131, 31, v130
	v_lshlrev_b64 v[130:131], 6, v[130:131]
	v_lshl_add_u64 v[130:131], s[62:63], 0, v[130:131]
	global_store_dwordx4 v[130:131], v[108:111], off
	global_store_dwordx4 v[130:131], v[104:107], off offset:16
	global_store_dwordx4 v[130:131], v[100:103], off offset:32
	global_store_dwordx4 v[130:131], v[96:99], off offset:48
	v_or_b32_e32 v130, 32, v128
	v_ashrrev_i32_e32 v131, 31, v130
	v_lshlrev_b64 v[130:131], 6, v[130:131]
	v_lshl_add_u64 v[130:131], s[62:63], 0, v[130:131]
	global_store_dwordx4 v[130:131], v[92:95], off
	global_store_dwordx4 v[130:131], v[88:91], off offset:16
	global_store_dwordx4 v[130:131], v[84:87], off offset:32
	global_store_dwordx4 v[130:131], v[80:83], off offset:48
	v_or_b32_e32 v130, 48, v128
	v_ashrrev_i32_e32 v131, 31, v130
	v_lshlrev_b64 v[130:131], 6, v[130:131]
	v_lshl_add_u64 v[130:131], s[62:63], 0, v[130:131]
	global_store_dwordx4 v[130:131], v[76:79], off
	global_store_dwordx4 v[130:131], v[72:75], off offset:16
	global_store_dwordx4 v[130:131], v[68:71], off offset:32
	global_store_dwordx4 v[130:131], v[64:67], off offset:48
	v_or_b32_e32 v130, 64, v128
	v_ashrrev_i32_e32 v131, 31, v130
	v_lshlrev_b64 v[130:131], 6, v[130:131]
	v_lshl_add_u64 v[130:131], s[62:63], 0, v[130:131]
	global_store_dwordx4 v[130:131], v[60:63], off
	global_store_dwordx4 v[130:131], v[56:59], off offset:16
	global_store_dwordx4 v[130:131], v[52:55], off offset:32
	global_store_dwordx4 v[130:131], v[48:51], off offset:48
	v_or_b32_e32 v130, 0x50, v128
	v_ashrrev_i32_e32 v131, 31, v130
	v_lshlrev_b64 v[130:131], 6, v[130:131]
	v_lshl_add_u64 v[130:131], s[62:63], 0, v[130:131]
	global_store_dwordx4 v[130:131], v[44:47], off
	global_store_dwordx4 v[130:131], v[40:43], off offset:16
	global_store_dwordx4 v[130:131], v[36:39], off offset:32
	global_store_dwordx4 v[130:131], v[32:35], off offset:48
	v_or_b32_e32 v130, 0x60, v128
	v_or_b32_e32 v128, 0x70, v128
	v_ashrrev_i32_e32 v131, 31, v130
	v_ashrrev_i32_e32 v129, 31, v128
	v_lshlrev_b64 v[130:131], 6, v[130:131]
	v_lshlrev_b64 v[128:129], 6, v[128:129]
	v_lshl_add_u64 v[130:131], s[62:63], 0, v[130:131]
	v_lshl_add_u64 v[128:129], s[62:63], 0, v[128:129]
	global_store_dwordx4 v[130:131], v[28:31], off
	global_store_dwordx4 v[130:131], v[24:27], off offset:16
	global_store_dwordx4 v[130:131], v[20:23], off offset:32
	global_store_dwordx4 v[130:131], v[16:19], off offset:48
	global_store_dwordx4 v[128:129], v[12:15], off
	global_store_dwordx4 v[128:129], v[8:11], off offset:16
	global_store_dwordx4 v[128:129], v[4:7], off offset:32
	global_store_dwordx4 v[128:129], v[0:3], off offset:48

; __device__ __forceinline__ bf16x8 gld16(const void* p) { bf16x8 v; asm volatile("global_load_dwordx4 %0, %1, off" : "=v"(v) : "v"(p) : "memory"); return v; }
;   __device__ __forceinline__ bfu* pb() const { return (bfu*)(b + L::o_pb); }
;   __device__ __forceinline__ float* gl() const { return (float*)(b + L::o_gl); }
;   __device__ __forceinline__ bfu* rb() const { return (bfu*)(b + L::o_rb); }
; template <bool SWAP>
; __device__ __forceinline__ void gemm_big(const bfu* __restrict__ A, int lda, const bfu* __restrict__ B, int ldb, int K,
;                                          f32x4 (&acc)[8][4], bfu* sm, const bfu* An = nullptr, const bfu* Bn = nullptr) {
;     ...
;   const int lrow = tid >> 2, lch = (tid & 3) * 8;
;   const bfu* Ap = A + (size_t)lrow * lda + lch;
;   const bfu* Bp = B + (size_t)lrow * ldb + lch;
;   int brow = lrow;
;   if (SWAP) brow = ((lrow & 12) << 2) | ((lrow >> 2) & 12) | (lrow & 3);
;   const int nk = K >> 5;
;   const bool chain = (An != nullptr);
;   const bfu* Apn = chain ? (An + (size_t)lrow * lda + lch) : Ap;
;   const bfu* Bpn = chain ? (Bn + (size_t)lrow * ldb + lch) : Bp;
;   auto gl = [&](bf16x8 (&ra)[4], bf16x8 (&rb)[2], int kt) {
;     const bool nx = (kt >= nk);
;     const bfu* pa = nx ? (chain ? Apn + (kt - nk) * 32 : Ap + (nk - 1) * 32) : Ap + kt * 32;
;     const bfu* pb = nx ? (chain ? Bpn + (kt - nk) * 32 : Bp + (nk - 1) * 32) : Bp + kt * 32;
; #pragma unroll
;     for (int q = 0; q < 4; ++q) ra[q] = gld16(pa + (size_t)(64 * q) * lda);
; #pragma unroll
;     for (int q = 0; q < 2; ++q) rb[q] = gld16(pb + (size_t)(64 * q) * ldb);
;   };
;   auto wt = [&](bf16x8 (&ra)[4], bf16x8 (&rb)[2]) {
;     asm volatile("s_waitcnt vmcnt(6)" : "+v"(ra[0]), "+v"(ra[1]), "+v"(ra[2]), "+v"(ra[3]), "+v"(rb[0]), "+v"(rb[1]) : : "memory");
;   };
;   auto st = [&](const bf16x8 (&ra)[4], const bf16x8 (&rb)[2], int buf) {
; #pragma unroll
;     for (int q = 0; q < 4; ++q) *(bf16x8*)(As + (buf * 256 + lrow + 64 * q) * 40 + lch) = ra[q];
; #pragma unroll
;     for (int q = 0; q < 2; ++q) *(bf16x8*)(Bs + (buf * 128 + brow + 64 * q) * 40 + lch) = rb[q];
;     ...
;   gl(ra0, rb0, 0);
;   gl(ra1, rb1, 1);
;   __syncthreads();
;   wt(ra0, rb0);
;   st(ra0, rb0, 0);
;   __syncthreads();
.LBB0_131:
	v_mov_b32_e32 v34, v174
	s_mov_b64 s[0:1], 0x20040
	v_ashrrev_i32_e32 v24, 2, v34
	v_ashrrev_i32_e32 v25, 31, v24
	v_lshlrev_b64 v[0:1], 11, v[24:25]
	v_lshlrev_b32_e32 v4, 4, v34
	v_lshl_add_u64 v[2:3], s[18:19], 0, v[0:1]
	v_and_b32_e32 v152, 48, v4
	v_lshl_add_u64 v[164:165], v[2:3], 0, v[152:153]
	v_lshl_add_u64 v[2:3], s[20:21], 0, v[0:1]
	v_lshl_add_u64 v[166:167], v[2:3], 0, v[152:153]
	v_lshl_add_u64 v[2:3], s[22:23], 0, v[0:1]
	v_lshl_add_u64 v[0:1], s[24:25], 0, v[0:1]
	v_lshl_add_u64 v[26:27], v[2:3], 0, v[152:153]
	v_lshl_add_u64 v[28:29], v[0:1], 0, v[152:153]
	global_load_dwordx4 v[0:3], v[164:165], off
	v_lshl_add_u64 v[4:5], v[164:165], 0, s[8:9]
	global_load_dwordx4 v[4:7], v[4:5], off
	v_lshl_add_u64 v[8:9], v[164:165], 0, s[4:5]
	global_load_dwordx4 v[8:11], v[8:9], off
	v_lshl_add_u64 v[12:13], v[164:165], 0, s[90:91]
	global_load_dwordx4 v[12:15], v[12:13], off
	global_load_dwordx4 v[16:19], v[166:167], off
	v_lshl_add_u64 v[20:21], v[166:167], 0, s[8:9]
	global_load_dwordx4 v[20:23], v[20:21], off
	v_lshl_add_u64 v[30:31], v[164:165], 0, 64
	global_load_dwordx4 v[48:51], v[30:31], off
	v_lshl_add_u64 v[30:31], v[164:165], 0, s[0:1]
	global_load_dwordx4 v[56:59], v[30:31], off
	s_mov_b64 s[18:19], 0x40040
	v_lshl_add_u64 v[30:31], v[164:165], 0, s[18:19]
	global_load_dwordx4 v[60:63], v[30:31], off
	s_mov_b64 s[18:19], 0x60040
	v_lshl_add_u64 v[30:31], v[164:165], 0, s[18:19]
	global_load_dwordx4 v[68:71], v[30:31], off
	v_lshl_add_u64 v[32:33], v[166:167], 0, 64
	global_load_dwordx4 v[72:75], v[32:33], off
	v_lshl_add_u64 v[30:31], v[166:167], 0, s[0:1]
	global_load_dwordx4 v[80:83], v[30:31], off
	s_barrier
	s_waitcnt vmcnt(6)
	s_movk_i32 s2, 0x40
	v_and_b32_e32 v36, 8, v24
	v_mul_u32_u24_e32 v36, 6, v36
	s_nop 0
	v_xor_b32_e32 v36, v152, v36
	v_mad_u32_u24 v168, v24, s2, v36
	ds_write_b128 v168, v[0:3]
	ds_write_b128 v168, v[4:7] offset:4096
	ds_write_b128 v168, v[8:11] offset:8192
	ds_write_b128 v168, v[12:15] offset:12288
	ds_write_b128 v168, v[16:19] offset:32768
	ds_write_b128 v168, v[20:23] offset:36864
	v_and_b32_e32 v0, 0x4f, v34
	v_and_b32_e32 v1, 0xfffff8f, v34
	v_mul_u32_u24_e32 v2, 32, v0
	v_and_b32_e32 v0, 48, v34
	v_and_b32_e32 v36, 8, v34
	v_mul_u32_u24_e32 v36, 6, v36
	s_nop 0
	v_xor_b32_e32 v0, v0, v36
	v_lshl_add_u32 v169, v2, 1, v0
	v_mad_u32_u24 v172, v1, s2, v0
	v_mov_b32_e32 v0, 0
	v_cndmask_b32_e64 v157, v27, v165, s[10:11]
	v_cndmask_b32_e64 v152, v26, v164, s[10:11]
	v_cndmask_b32_e64 v159, v29, v167, s[10:11]
	v_cndmask_b32_e64 v170, v28, v166, s[10:11]
	s_mov_b32 s17, 0
	s_movk_i32 s15, 0xfc40
	v_mov_b32_e32 v1, v0
	v_mov_b32_e32 v2, v0
	v_mov_b32_e32 v3, v0
	v_mov_b32_e32 v4, v0
	v_mov_b32_e32 v5, v0
	v_mov_b32_e32 v6, v0
	v_mov_b32_e32 v7, v0
	v_mov_b32_e32 v8, v0
	v_mov_b32_e32 v9, v0
	v_mov_b32_e32 v10, v0
	v_mov_b32_e32 v11, v0
	v_mov_b32_e32 v12, v0
	v_mov_b32_e32 v13, v0
	v_mov_b32_e32 v14, v0
	v_mov_b32_e32 v15, v0
	v_mov_b32_e32 v16, v0
	v_mov_b32_e32 v17, v0
	v_mov_b32_e32 v18, v0
	v_mov_b32_e32 v19, v0
	v_mov_b32_e32 v20, v0
	v_mov_b32_e32 v21, v0
	v_mov_b32_e32 v22, v0
	v_mov_b32_e32 v23, v0
	v_mov_b32_e32 v24, v0
	v_mov_b32_e32 v25, v0
	v_mov_b32_e32 v26, v0
	v_mov_b32_e32 v27, v0
	v_mov_b32_e32 v28, v0
	v_mov_b32_e32 v29, v0
	v_mov_b32_e32 v30, v0
	v_mov_b32_e32 v31, v0
	v_mov_b32_e32 v32, v0
	v_mov_b32_e32 v33, v0
	v_mov_b32_e32 v34, v0
	v_mov_b32_e32 v35, v0
	v_mov_b32_e32 v36, v0
	v_mov_b32_e32 v37, v0
	v_mov_b32_e32 v38, v0
	v_mov_b32_e32 v39, v0
	v_mov_b32_e32 v40, v0
	v_mov_b32_e32 v41, v0
	v_mov_b32_e32 v42, v0
	v_mov_b32_e32 v43, v0
	v_mov_b32_e32 v44, v0
	v_mov_b32_e32 v45, v0
	v_mov_b32_e32 v46, v0
	v_mov_b32_e32 v47, v0
	v_mov_b32_e32 v52, v0
	v_mov_b32_e32 v53, v0
	v_mov_b32_e32 v54, v0
	v_mov_b32_e32 v55, v0
	v_mov_b32_e32 v64, v0
	v_mov_b32_e32 v65, v0
	v_mov_b32_e32 v66, v0
	v_mov_b32_e32 v67, v0
	v_mov_b32_e32 v76, v0
	v_mov_b32_e32 v77, v0
	v_mov_b32_e32 v78, v0
	v_mov_b32_e32 v79, v0
	v_mov_b32_e32 v84, v0
	v_mov_b32_e32 v85, v0
	v_mov_b32_e32 v86, v0
	v_mov_b32_e32 v87, v0
	v_mov_b32_e32 v88, v0
	v_mov_b32_e32 v89, v0
	v_mov_b32_e32 v90, v0
	v_mov_b32_e32 v91, v0
	v_mov_b32_e32 v92, v0
	v_mov_b32_e32 v93, v0
	v_mov_b32_e32 v94, v0
	v_mov_b32_e32 v95, v0
	v_mov_b32_e32 v96, v0
	v_mov_b32_e32 v97, v0
	v_mov_b32_e32 v98, v0
	v_mov_b32_e32 v99, v0
	v_mov_b32_e32 v100, v0
	v_mov_b32_e32 v101, v0
	v_mov_b32_e32 v102, v0
	v_mov_b32_e32 v103, v0
	v_mov_b32_e32 v104, v0
	v_mov_b32_e32 v105, v0
	v_mov_b32_e32 v106, v0
	v_mov_b32_e32 v107, v0
	v_mov_b32_e32 v108, v0
	v_mov_b32_e32 v109, v0
	v_mov_b32_e32 v110, v0
	v_mov_b32_e32 v111, v0
	v_mov_b32_e32 v112, v0
	v_mov_b32_e32 v113, v0
	v_mov_b32_e32 v114, v0
	v_mov_b32_e32 v115, v0
	v_mov_b32_e32 v116, v0
	v_mov_b32_e32 v117, v0
	v_mov_b32_e32 v118, v0
	v_mov_b32_e32 v119, v0
	v_mov_b32_e32 v120, v0
	v_mov_b32_e32 v121, v0
	v_mov_b32_e32 v122, v0
	v_mov_b32_e32 v123, v0
	v_mov_b32_e32 v124, v0
	v_mov_b32_e32 v125, v0
	v_mov_b32_e32 v126, v0
	v_mov_b32_e32 v127, v0
	v_mov_b32_e32 v128, v0
	v_mov_b32_e32 v129, v0
	v_mov_b32_e32 v130, v0
	v_mov_b32_e32 v131, v0
	v_mov_b32_e32 v132, v0
	v_mov_b32_e32 v133, v0
	v_mov_b32_e32 v134, v0
	v_mov_b32_e32 v135, v0
	v_mov_b32_e32 v136, v0
	v_mov_b32_e32 v137, v0
	v_mov_b32_e32 v138, v0
	v_mov_b32_e32 v139, v0
	v_mov_b32_e32 v140, v0
	v_mov_b32_e32 v141, v0
	v_mov_b32_e32 v142, v0
	v_mov_b32_e32 v143, v0
	v_mov_b32_e32 v144, v0
	v_mov_b32_e32 v145, v0
	v_mov_b32_e32 v146, v0
	v_mov_b32_e32 v147, v0
	v_mov_b32_e32 v148, v0
	v_mov_b32_e32 v149, v0
	v_mov_b32_e32 v150, v0
	v_mov_b32_e32 v151, v0
	s_waitcnt lgkmcnt(0)
	s_barrier
; #define MFMA16(a, b, c) __builtin_amdgcn_mfma_f32_16x16x32_bf16((a), (b), (c), 0, 0, 0)
; __device__ __forceinline__ bf16x8 gld16(const void* p) { bf16x8 v; asm volatile("global_load_dwordx4 %0, %1, off" : "=v"(v) : "v"(p) : "memory"); return v; }
; template <bool SWAP>
; __device__ __forceinline__ void gemm_big(const bfu* __restrict__ A, int lda, const bfu* __restrict__ B, int ldb, int K,
;                                          f32x4 (&acc)[8][4], bfu* sm, const bfu* An = nullptr, const bfu* Bn = nullptr) {
;     ...
;   auto gl = [&](bf16x8 (&ra)[4], bf16x8 (&rb)[2], int kt) {
;     const bool nx = (kt >= nk);
;     const bfu* pa = nx ? (chain ? Apn + (kt - nk) * 32 : Ap + (nk - 1) * 32) : Ap + kt * 32;
;     const bfu* pb = nx ? (chain ? Bpn + (kt - nk) * 32 : Bp + (nk - 1) * 32) : Bp + kt * 32;
; #pragma unroll
;     for (int q = 0; q < 4; ++q) ra[q] = gld16(pa + (size_t)(64 * q) * lda);
; #pragma unroll
;     for (int q = 0; q < 2; ++q) rb[q] = gld16(pb + (size_t)(64 * q) * ldb);
;   };
;   auto wt = [&](bf16x8 (&ra)[4], bf16x8 (&rb)[2]) {
;     asm volatile("s_waitcnt vmcnt(6)" : "+v"(ra[0]), "+v"(ra[1]), "+v"(ra[2]), "+v"(ra[3]), "+v"(rb[0]), "+v"(rb[1]) : : "memory");
;   };
;   auto st = [&](const bf16x8 (&ra)[4], const bf16x8 (&rb)[2], int buf) {
; #pragma unroll
;     for (int q = 0; q < 4; ++q) *(bf16x8*)(As + (buf * 256 + lrow + 64 * q) * 40 + lch) = ra[q];
; #pragma unroll
;     for (int q = 0; q < 2; ++q) *(bf16x8*)(Bs + (buf * 128 + brow + 64 * q) * 40 + lch) = rb[q];
;   };
;   auto comp = [&](int buf, auto&& mid) {
;     const bfu* as = As + buf * 256 * 40 + (wr * 128 + c15) * 40 + g * 8;
;     const bfu* bs = Bs + buf * 128 * 40 + (wc * 64 + c15) * 40 + g * 8;
;     bf16x8 b[4];
; #pragma unroll
;     for (int j = 0; j < 4; ++j) b[j] = *(const bf16x8*)(bs + j * 16 * 40);
;     {
;       bf16x8 a[4];
; #pragma unroll
;       for (int i = 0; i < 4; ++i) a[i] = *(const bf16x8*)(as + i * 16 * 40);
;       mid();
;       __builtin_amdgcn_s_setprio(1);
; #pragma unroll
;       for (int i = 0; i < 4; ++i)
; #pragma unroll
;         for (int j = 0; j < 4; ++j) acc[i][j] = SWAP ? MFMA16(b[j], a[i], acc[i][j]) : MFMA16(a[i], b[j], acc[i][j]);
;       __builtin_amdgcn_s_setprio(0);
;     }
;     ...
;   for (int kt = 0; kt < nk; kt += 2) {
;     gl(ra0, rb0, kt + 2);
;     comp(0, [&]() { wt(ra1, rb1); st(ra1, rb1, 1); });
;     __syncthreads();
.LBB0_132:
	s_add_i32 s18, s17, 2
	s_cmp_lt_u32 s17, 30
	s_cselect_b64 s[0:1], -1, 0
	s_add_i32 s2, s15, 0x400
	s_and_b64 s[20:21], s[10:11], exec
	s_cselect_b32 s19, 0x3e0, s15
	s_and_b64 vcc, s[0:1], exec
	s_cselect_b32 s2, s2, s19
	v_cndmask_b32_e64 v201, v157, v165, s[0:1]
	v_cndmask_b32_e64 v200, v152, v164, s[0:1]
	v_cndmask_b32_e64 v203, v159, v167, s[0:1]
	v_cndmask_b32_e64 v202, v170, v166, s[0:1]
	s_lshl_b64 s[0:1], s[2:3], 1
	v_lshl_add_u64 v[212:213], v[200:201], 0, s[0:1]
	v_lshl_add_u64 v[220:221], v[202:203], 0, s[0:1]
	ds_read_b128 v[224:227], v169 offset:32768
	ds_read_b128 v[228:231], v169 offset:33792
	ds_read_b128 v[232:235], v169 offset:34816
	ds_read_b128 v[236:239], v169 offset:35840
	ds_read_b128 v[240:243], v172
	ds_read_b128 v[244:247], v172 offset:1024
	ds_read_b128 v[248:251], v172 offset:2048
	ds_read_b128 v[184:187], v172 offset:3072
	s_waitcnt vmcnt(0)
	ds_write_b128 v168, v[48:51] offset:16384
	ds_write_b128 v168, v[56:59] offset:20480
	ds_write_b128 v168, v[60:63] offset:24576
	ds_write_b128 v168, v[68:71] offset:28672
	ds_write_b128 v168, v[72:75] offset:40960
	ds_write_b128 v168, v[80:83] offset:45056
	s_cmp_lt_u32 s17, 29
	s_cselect_b64 s[0:1], -1, 0
	s_add_i32 s2, s15, 0x420
	s_add_i32 s17, s15, 32
	s_and_b64 s[20:21], s[10:11], exec
	s_cselect_b32 s17, 0x3e0, s17
	s_and_b64 s[20:21], s[0:1], exec
	s_cselect_b32 s2, s2, s17
	v_cndmask_b32_e64 v49, v157, v165, s[0:1]
	v_cndmask_b32_e64 v48, v152, v164, s[0:1]
	v_cndmask_b32_e64 v51, v159, v167, s[0:1]
	v_cndmask_b32_e64 v50, v170, v166, s[0:1]
	s_lshl_b64 s[0:1], s[2:3], 1
	v_lshl_add_u64 v[68:69], v[48:49], 0, s[0:1]
	v_lshl_add_u64 v[80:81], v[50:51], 0, s[0:1]
	s_setprio 1
	s_waitcnt lgkmcnt(9)
	v_mfma_f32_16x16x32_bf16 v[148:151], v[240:243], v[224:227], v[148:151]
	global_load_dwordx4 v[200:203], v[212:213], off
	v_mfma_f32_16x16x32_bf16 v[144:147], v[240:243], v[228:231], v[144:147]
	global_load_dwordx4 v[48:51], v[68:69], off
	v_mfma_f32_16x16x32_bf16 v[140:143], v[240:243], v[232:235], v[140:143]
	v_lshl_add_u64 v[204:205], v[212:213], 0, s[8:9]
	global_load_dwordx4 v[204:207], v[204:205], off
	v_mfma_f32_16x16x32_bf16 v[136:139], v[240:243], v[236:239], v[136:139]
	v_lshl_add_u64 v[56:57], v[68:69], 0, s[8:9]
	global_load_dwordx4 v[56:59], v[56:57], off
	s_waitcnt lgkmcnt(8)
	v_mfma_f32_16x16x32_bf16 v[132:135], v[244:247], v[224:227], v[132:135]
	v_lshl_add_u64 v[208:209], v[212:213], 0, s[4:5]
	global_load_dwordx4 v[208:211], v[208:209], off
	v_mfma_f32_16x16x32_bf16 v[128:131], v[244:247], v[228:231], v[128:131]
	v_lshl_add_u64 v[60:61], v[68:69], 0, s[4:5]
	global_load_dwordx4 v[60:63], v[60:61], off
	v_mfma_f32_16x16x32_bf16 v[124:127], v[244:247], v[232:235], v[124:127]
	v_lshl_add_u64 v[212:213], v[212:213], 0, s[90:91]
	global_load_dwordx4 v[212:215], v[212:213], off
	v_mfma_f32_16x16x32_bf16 v[120:123], v[244:247], v[236:239], v[120:123]
	v_lshl_add_u64 v[68:69], v[68:69], 0, s[90:91]
	global_load_dwordx4 v[68:71], v[68:69], off
	s_waitcnt lgkmcnt(7)
	v_mfma_f32_16x16x32_bf16 v[116:119], v[248:251], v[224:227], v[116:119]
	global_load_dwordx4 v[216:219], v[220:221], off
	v_mfma_f32_16x16x32_bf16 v[112:115], v[248:251], v[228:231], v[112:115]
	global_load_dwordx4 v[72:75], v[80:81], off
	v_mfma_f32_16x16x32_bf16 v[108:111], v[248:251], v[232:235], v[108:111]
	v_lshl_add_u64 v[220:221], v[220:221], 0, s[8:9]
	global_load_dwordx4 v[220:223], v[220:221], off
	v_mfma_f32_16x16x32_bf16 v[104:107], v[248:251], v[236:239], v[104:107]
	v_lshl_add_u64 v[80:81], v[80:81], 0, s[8:9]
	global_load_dwordx4 v[80:83], v[80:81], off
	s_waitcnt lgkmcnt(6)
	v_mfma_f32_16x16x32_bf16 v[100:103], v[184:187], v[224:227], v[100:103]
	v_mfma_f32_16x16x32_bf16 v[96:99], v[184:187], v[228:231], v[96:99]
	v_mfma_f32_16x16x32_bf16 v[92:95], v[184:187], v[232:235], v[92:95]
	v_mfma_f32_16x16x32_bf16 v[88:91], v[184:187], v[236:239], v[88:91]
	s_setprio 0
	ds_read_b128 v[240:243], v172 offset:4096
	ds_read_b128 v[244:247], v172 offset:5120
	ds_read_b128 v[248:251], v172 offset:6144
	ds_read_b128 v[184:187], v172 offset:7168
	s_setprio 1
	s_waitcnt lgkmcnt(3)
	v_mfma_f32_16x16x32_bf16 v[84:87], v[240:243], v[224:227], v[84:87]
	v_mfma_f32_16x16x32_bf16 v[76:79], v[240:243], v[228:231], v[76:79]
	v_mfma_f32_16x16x32_bf16 v[64:67], v[240:243], v[232:235], v[64:67]
	v_mfma_f32_16x16x32_bf16 v[52:55], v[240:243], v[236:239], v[52:55]
	s_waitcnt lgkmcnt(2)
	v_mfma_f32_16x16x32_bf16 v[44:47], v[244:247], v[224:227], v[44:47]
	v_mfma_f32_16x16x32_bf16 v[40:43], v[244:247], v[228:231], v[40:43]
	v_mfma_f32_16x16x32_bf16 v[36:39], v[244:247], v[232:235], v[36:39]
	v_mfma_f32_16x16x32_bf16 v[32:35], v[244:247], v[236:239], v[32:35]
	s_waitcnt lgkmcnt(1)
	v_mfma_f32_16x16x32_bf16 v[28:31], v[248:251], v[224:227], v[28:31]
	v_mfma_f32_16x16x32_bf16 v[24:27], v[248:251], v[228:231], v[24:27]
	v_mfma_f32_16x16x32_bf16 v[20:23], v[248:251], v[232:235], v[20:23]
	v_mfma_f32_16x16x32_bf16 v[16:19], v[248:251], v[236:239], v[16:19]
	s_waitcnt lgkmcnt(0)
	v_mfma_f32_16x16x32_bf16 v[12:15], v[184:187], v[224:227], v[12:15]
	v_mfma_f32_16x16x32_bf16 v[8:11], v[184:187], v[228:231], v[8:11]
	v_mfma_f32_16x16x32_bf16 v[4:7], v[184:187], v[232:235], v[4:7]
	v_mfma_f32_16x16x32_bf16 v[0:3], v[184:187], v[236:239], v[0:3]
	s_setprio 0
	s_barrier
; #define MFMA16(a, b, c) __builtin_amdgcn_mfma_f32_16x16x32_bf16((a), (b), (c), 0, 0, 0)
;   __device__ __forceinline__ float* gl() const { return (float*)(b + L::o_gl); }
; template <bool SWAP>
; __device__ __forceinline__ void gemm_big(const bfu* __restrict__ A, int lda, const bfu* __restrict__ B, int ldb, int K,
;                                          f32x4 (&acc)[8][4], bfu* sm, const bfu* An = nullptr, const bfu* Bn = nullptr) {
;     ...
;     {
;       bf16x8 a[4];
; #pragma unroll
;       for (int i = 0; i < 4; ++i) a[i] = *(const bf16x8*)(as + (i + 4) * 16 * 40);
;       __builtin_amdgcn_s_setprio(1);
; #pragma unroll
;       for (int i = 0; i < 4; ++i)
; #pragma unroll
;         for (int j = 0; j < 4; ++j) acc[i + 4][j] = SWAP ? MFMA16(b[j], a[i], acc[i + 4][j]) : MFMA16(a[i], b[j], acc[i + 4][j]);
;       __builtin_amdgcn_s_setprio(0);
;     }
;   };
;     ...
;     gl(ra1, rb1, kt + 3);
;     comp(1, [&]() { wt(ra0, rb0); st(ra0, rb0, 0); });
;     __syncthreads();
;   }
	ds_read_b128 v[184:187], v169 offset:40960
	ds_read_b128 v[224:227], v169 offset:41984
	ds_read_b128 v[228:231], v169 offset:43008
	ds_read_b128 v[232:235], v169 offset:44032
	ds_read_b128 v[236:239], v172 offset:16384
	ds_read_b128 v[240:243], v172 offset:17408
	ds_read_b128 v[244:247], v172 offset:18432
	ds_read_b128 v[248:251], v172 offset:19456
	s_setprio 1
	s_waitcnt lgkmcnt(3)
	v_mfma_f32_16x16x32_bf16 v[148:151], v[236:239], v[184:187], v[148:151]
	v_mfma_f32_16x16x32_bf16 v[144:147], v[236:239], v[224:227], v[144:147]
	v_mfma_f32_16x16x32_bf16 v[140:143], v[236:239], v[228:231], v[140:143]
	v_mfma_f32_16x16x32_bf16 v[136:139], v[236:239], v[232:235], v[136:139]
	s_waitcnt lgkmcnt(2)
	v_mfma_f32_16x16x32_bf16 v[132:135], v[240:243], v[184:187], v[132:135]
	v_mfma_f32_16x16x32_bf16 v[128:131], v[240:243], v[224:227], v[128:131]
	v_mfma_f32_16x16x32_bf16 v[124:127], v[240:243], v[228:231], v[124:127]
	v_mfma_f32_16x16x32_bf16 v[120:123], v[240:243], v[232:235], v[120:123]
	s_waitcnt lgkmcnt(1)
	v_mfma_f32_16x16x32_bf16 v[116:119], v[244:247], v[184:187], v[116:119]
	v_mfma_f32_16x16x32_bf16 v[112:115], v[244:247], v[224:227], v[112:115]
	v_mfma_f32_16x16x32_bf16 v[108:111], v[244:247], v[228:231], v[108:111]
	v_mfma_f32_16x16x32_bf16 v[104:107], v[244:247], v[232:235], v[104:107]
	s_waitcnt lgkmcnt(0)
	v_mfma_f32_16x16x32_bf16 v[100:103], v[248:251], v[184:187], v[100:103]
	v_mfma_f32_16x16x32_bf16 v[96:99], v[248:251], v[224:227], v[96:99]
	v_mfma_f32_16x16x32_bf16 v[92:95], v[248:251], v[228:231], v[92:95]
	v_mfma_f32_16x16x32_bf16 v[88:91], v[248:251], v[232:235], v[88:91]
	s_setprio 0
	s_waitcnt vmcnt(1)
	ds_write_b128 v168, v[200:203]
	ds_write_b128 v168, v[204:207] offset:4096
	ds_write_b128 v168, v[208:211] offset:8192
	ds_write_b128 v168, v[212:215] offset:12288
	ds_write_b128 v168, v[216:219] offset:32768
	ds_write_b128 v168, v[220:223] offset:36864
	ds_read_b128 v[236:239], v172 offset:20480
	ds_read_b128 v[240:243], v172 offset:21504
	ds_read_b128 v[244:247], v172 offset:22528
	ds_read_b128 v[248:251], v172 offset:23552
	s_setprio 1
	s_waitcnt lgkmcnt(3)
	v_mfma_f32_16x16x32_bf16 v[84:87], v[236:239], v[184:187], v[84:87]
	v_mfma_f32_16x16x32_bf16 v[76:79], v[236:239], v[224:227], v[76:79]
	v_mfma_f32_16x16x32_bf16 v[64:67], v[236:239], v[228:231], v[64:67]
	v_mfma_f32_16x16x32_bf16 v[52:55], v[236:239], v[232:235], v[52:55]
	s_waitcnt lgkmcnt(2)
	v_mfma_f32_16x16x32_bf16 v[44:47], v[240:243], v[184:187], v[44:47]
	v_mfma_f32_16x16x32_bf16 v[40:43], v[240:243], v[224:227], v[40:43]
	v_mfma_f32_16x16x32_bf16 v[36:39], v[240:243], v[228:231], v[36:39]
	v_mfma_f32_16x16x32_bf16 v[32:35], v[240:243], v[232:235], v[32:35]
	s_waitcnt lgkmcnt(1)
	v_mfma_f32_16x16x32_bf16 v[28:31], v[244:247], v[184:187], v[28:31]
	v_mfma_f32_16x16x32_bf16 v[24:27], v[244:247], v[224:227], v[24:27]
	v_mfma_f32_16x16x32_bf16 v[20:23], v[244:247], v[228:231], v[20:23]
	v_mfma_f32_16x16x32_bf16 v[16:19], v[244:247], v[232:235], v[16:19]
	s_waitcnt lgkmcnt(0)
	v_mfma_f32_16x16x32_bf16 v[12:15], v[248:251], v[184:187], v[12:15]
	v_mfma_f32_16x16x32_bf16 v[8:11], v[248:251], v[224:227], v[8:11]
	v_mfma_f32_16x16x32_bf16 v[4:7], v[248:251], v[228:231], v[4:7]
	v_mfma_f32_16x16x32_bf16 v[0:3], v[248:251], v[232:235], v[0:3]
	s_setprio 0
	s_add_i32 s15, s15, 64
	s_mov_b32 s17, s18
	s_barrier
	s_cbranch_vccnz .LBB0_132
;   __device__ __forceinline__ bfu* VtC() const { return (bfu*)(b + L::o_VtC); }
;   __device__ __forceinline__ bfu* VtD() const { return (bfu*)(b + L::o_VtD); }
;   __device__ __forceinline__ bfu* rb() const { return (bfu*)(b + L::o_rb); }
; template <int G>
; __device__ __forceinline__ void p1_big(const Params& P, const Ptrs<G>& w, int layer, int mt, int nt, bfu* sm, int mtn, int ntn) {
;     ...
;     bfu* dst = (n0 < 7168) ? w.VtC() : w.VtD();
;     const int cofs = (n0 < 7168) ? (n0 - 6656) : (n0 - 7168);
; #pragma unroll
;     for (int i = 0; i < 8; ++i)
; #pragma unroll
;       for (int j = 0; j < 4; ++j) {
;         int rb = m0 + wr * 128 + i * 16 + g * 4; int c = cofs + wc * 64 + j * 16 + c15;
;         int seq = rb >> 13, t = rb & 8191, h = c >> 6, d = c & 63;
;         uint2 o; o.x = pack2(acc[i][j][0], acc[i][j][1]); o.y = pack2(acc[i][j][2], acc[i][j][3]);
;         *(uint2*)(dst + ((size_t)((seq * 8 + h) * 64 + d)) * TSEQ + t) = o;
;       }
	s_cmp_lt_u32 s35, 56
	s_cselect_b64 s[0:1], -1, 0
	s_waitcnt vmcnt(0)
	s_and_b64 s[0:1], s[0:1], exec
	s_movk_i32 s0, 0xe600
	v_and_b32_e32 v48, 0xffffff80, v198
	s_cselect_b32 s2, s0, 0xffffe400
	v_add_u32_e32 v48, s16, v48
	v_or_b32_e32 v50, s14, v171
	s_mov_b32 s0, 0x18121800
	v_readlane_b32 s20, v253, 38
	v_and_b32_e32 v49, 0x1f80, v48
	v_ashrrev_i32_e32 v48, 4, v48
	v_add_u32_e32 v50, s2, v50
	s_cselect_b32 s0, s0, 0x19121800
	v_readlane_b32 s22, v253, 40
	v_and_b32_e32 v48, 0xfffffe00, v48
	v_lshl_or_b32 v50, v161, 6, v50
	v_readlane_b32 s23, v253, 41
	s_add_u32 s0, s22, s0
	v_add_u32_e32 v48, v50, v48
	v_lshlrev_b32_e32 v49, 1, v49
	s_addc_u32 s1, s23, 0
	v_lshl_or_b32 v152, v163, 3, v49
	v_ashrrev_i32_e32 v49, 31, v48
	v_lshl_add_u64 v[50:51], s[0:1], 0, v[152:153]
	v_lshlrev_b64 v[56:57], 14, v[48:49]
	v_lshl_add_u64 v[56:57], v[50:51], 0, v[56:57]
	v_cvt_pk_bf16_f32 v59, v150, v151
	v_cvt_pk_bf16_f32 v58, v148, v149
	global_store_dwordx2 v[56:57], v[58:59], off
	v_or_b32_e32 v58, 16, v48
	v_ashrrev_i32_e32 v59, 31, v58
	v_lshlrev_b64 v[58:59], 14, v[58:59]
	v_lshl_add_u64 v[58:59], v[50:51], 0, v[58:59]
	v_cvt_pk_bf16_f32 v61, v146, v147
	v_cvt_pk_bf16_f32 v60, v144, v145
	global_store_dwordx2 v[58:59], v[60:61], off
	v_or_b32_e32 v60, 32, v48
	v_or_b32_e32 v48, 48, v48
	v_ashrrev_i32_e32 v61, 31, v60
	v_ashrrev_i32_e32 v49, 31, v48
	v_lshlrev_b64 v[60:61], 14, v[60:61]
	v_lshlrev_b64 v[48:49], 14, v[48:49]
	v_lshl_add_u64 v[60:61], v[50:51], 0, v[60:61]
	v_lshl_add_u64 v[48:49], v[50:51], 0, v[48:49]
	v_cvt_pk_bf16_f32 v51, v138, v139
	v_cvt_pk_bf16_f32 v50, v136, v137
	global_store_dwordx2 v[48:49], v[50:51], off
	v_cvt_pk_bf16_f32 v51, v134, v135
	v_cvt_pk_bf16_f32 v50, v132, v133
	global_store_dwordx2 v[56:57], v[50:51], off offset:32
	v_cvt_pk_bf16_f32 v51, v130, v131
	v_cvt_pk_bf16_f32 v50, v128, v129
	global_store_dwordx2 v[58:59], v[50:51], off offset:32
	v_cvt_pk_bf16_f32 v51, v126, v127
	v_cvt_pk_bf16_f32 v50, v124, v125
	global_store_dwordx2 v[60:61], v[50:51], off offset:32
	v_cvt_pk_bf16_f32 v51, v122, v123
	v_cvt_pk_bf16_f32 v50, v120, v121
	global_store_dwordx2 v[48:49], v[50:51], off offset:32
	v_cvt_pk_bf16_f32 v51, v118, v119
	v_cvt_pk_bf16_f32 v50, v116, v117
	global_store_dwordx2 v[56:57], v[50:51], off offset:64
	v_cvt_pk_bf16_f32 v51, v114, v115
	v_cvt_pk_bf16_f32 v50, v112, v113
	global_store_dwordx2 v[58:59], v[50:51], off offset:64
	v_cvt_pk_bf16_f32 v51, v110, v111
	v_cvt_pk_bf16_f32 v50, v108, v109
	global_store_dwordx2 v[60:61], v[50:51], off offset:64
	v_cvt_pk_bf16_f32 v51, v106, v107
	v_cvt_pk_bf16_f32 v50, v104, v105
	global_store_dwordx2 v[48:49], v[50:51], off offset:64
	v_cvt_pk_bf16_f32 v51, v102, v103
	v_cvt_pk_bf16_f32 v50, v100, v101
	global_store_dwordx2 v[56:57], v[50:51], off offset:96
	v_cvt_pk_bf16_f32 v51, v98, v99
	v_cvt_pk_bf16_f32 v50, v96, v97
	global_store_dwordx2 v[58:59], v[50:51], off offset:96
	v_cvt_pk_bf16_f32 v51, v94, v95
	v_cvt_pk_bf16_f32 v50, v92, v93
	global_store_dwordx2 v[60:61], v[50:51], off offset:96
	v_cvt_pk_bf16_f32 v51, v90, v91
	v_cvt_pk_bf16_f32 v50, v88, v89
	global_store_dwordx2 v[48:49], v[50:51], off offset:96
	v_cvt_pk_bf16_f32 v51, v86, v87
	v_cvt_pk_bf16_f32 v50, v84, v85
	global_store_dwordx2 v[56:57], v[50:51], off offset:128
	v_cvt_pk_bf16_f32 v51, v78, v79
	v_cvt_pk_bf16_f32 v50, v76, v77
	global_store_dwordx2 v[58:59], v[50:51], off offset:128
	v_cvt_pk_bf16_f32 v51, v66, v67
	v_cvt_pk_bf16_f32 v50, v64, v65
	v_cvt_pk_bf16_f32 v63, v142, v143
	v_cvt_pk_bf16_f32 v62, v140, v141
	global_store_dwordx2 v[60:61], v[50:51], off offset:128
	v_cvt_pk_bf16_f32 v51, v54, v55
	v_cvt_pk_bf16_f32 v50, v52, v53
	v_cvt_pk_bf16_f32 v47, v46, v47
	v_cvt_pk_bf16_f32 v46, v44, v45
	v_cvt_pk_bf16_f32 v43, v42, v43
	v_cvt_pk_bf16_f32 v42, v40, v41
	v_cvt_pk_bf16_f32 v39, v38, v39
	v_cvt_pk_bf16_f32 v38, v36, v37
	v_cvt_pk_bf16_f32 v35, v34, v35
	v_cvt_pk_bf16_f32 v34, v32, v33
	v_cvt_pk_bf16_f32 v31, v30, v31
	v_cvt_pk_bf16_f32 v30, v28, v29
	v_cvt_pk_bf16_f32 v27, v26, v27
	v_cvt_pk_bf16_f32 v26, v24, v25
	v_cvt_pk_bf16_f32 v23, v22, v23
	v_cvt_pk_bf16_f32 v22, v20, v21
	v_cvt_pk_bf16_f32 v19, v18, v19
	v_cvt_pk_bf16_f32 v18, v16, v17
	v_cvt_pk_bf16_f32 v15, v14, v15
	v_cvt_pk_bf16_f32 v14, v12, v13
	v_cvt_pk_bf16_f32 v11, v10, v11
	v_cvt_pk_bf16_f32 v10, v8, v9
	v_cvt_pk_bf16_f32 v7, v6, v7
	v_cvt_pk_bf16_f32 v6, v4, v5
	v_cvt_pk_bf16_f32 v3, v2, v3
	v_cvt_pk_bf16_f32 v2, v0, v1
	v_readlane_b32 s21, v253, 39
	global_store_dwordx2 v[60:61], v[62:63], off
	global_store_dwordx2 v[48:49], v[50:51], off offset:128
	global_store_dwordx2 v[56:57], v[46:47], off offset:160
	global_store_dwordx2 v[58:59], v[42:43], off offset:160
	global_store_dwordx2 v[60:61], v[38:39], off offset:160
	global_store_dwordx2 v[48:49], v[34:35], off offset:160
	global_store_dwordx2 v[56:57], v[30:31], off offset:192
	global_store_dwordx2 v[58:59], v[26:27], off offset:192
	global_store_dwordx2 v[60:61], v[22:23], off offset:192
	global_store_dwordx2 v[48:49], v[18:19], off offset:192
	global_store_dwordx2 v[56:57], v[14:15], off offset:224
	global_store_dwordx2 v[58:59], v[10:11], off offset:224
	global_store_dwordx2 v[60:61], v[6:7], off offset:224
	global_store_dwordx2 v[48:49], v[2:3], off offset:224
	s_branch .LBB0_106
